# head rescale table: 8 heads' statistics prefetched before the loop; mLSTM chunk barrier waits only for the chunk's loads, output stores drain in background
# speedup vs baseline: 1.0253x; 1.0040x over previous
; #define LAS __attribute__((address_space(3)))
; #define WG_BARRIER() do { asm volatile("s_waitcnt vmcnt(0) lgkmcnt(0)" ::: "memory"); __builtin_amdgcn_s_barrier(); asm volatile("" ::: "memory"); } while (0)
; #define ML_LOADG(c_) do { rli = *(const f32x2*)(gLI + (c_) * CH + 2 * lane); rlf = *(const f32x2*)(gLF + (c_) * CH + 2 * lane); } while (0)
; __device__ __forceinline__ void mlstm_phase(LAS unsigned char* lds, const bf16_t* Q, const bf16_t* Kn, const bf16_t* KT, const bf16_t* VT, const float* LI, const float* LF, bf16_t* HH, const bf16_t* O, float* SS) {
;     ...
;         const int xcd = item & 7, slot = item >> 3, eb = slot & 7, bh = xcd * 4 + (slot >> 3), hh = bh & 7, bb = bh >> 3;
;         WG_BARRIER();
;         for (int i = tid; i < 2 * 13056 / 4; i += 512) *(LAS unsigned*)(lds + L_CT + 4 * i) = 0u;
;         for (int i = tid; i < 16 * RS / 4; i += 512) *(LAS unsigned*)(lds + L_VT + 32 * RS + 4 * i) = (i < RS / 4) ? 0x3F803F80u : 0u;
;         const bf16_t* gQ = Q + (size_t)bb * SEQ * 1024 + hh * 128;
;         const bf16_t* gK = Kn + (size_t)bb * SEQ * 1024 + hh * 128;
;         const bf16_t* gKT = KT + (size_t)(bb * 8 + hh) * 128 * SEQ;
;         const bf16_t* gVT = VT + ((size_t)(bb * 8 + hh) * 256 + eb * 32) * SEQ;
;         const float* gLI = LI + (size_t)(bb * 8 + hh) * SEQ; const float* gLF = LF + (size_t)(bb * 8 + hh) * SEQ;
;         bf16_t* gH = HH + (size_t)bb * SEQ * DM + hh * 256 + eb * 32;
;         const bf16_t* gO = O + (size_t)bb * SEQ * DM + hh * 256 + eb * 32;
;         float* gSS = SS + (size_t)bb * SEQ * 64 + hh * 8 + eb;
;         u32x4 ro;
;         u32x4 rq[4], rk[4], rkt[4], rvt; f32x2 rli = {0.f, 0.f}, rlf = {0.f, 0.f};
;         const int prow = tid >> 4, pseg = tid & 15;
;         float m_prev = 0.f;
;     ...
;         ML_LOAD(0);
;         if (w == 0) { ML_LOADG(0); ML_SCALARS(0); ML_LOADG(1); }
;         f32x4 accC[2][3];
; #pragma unroll
;         for (int dd = 0; dd < 2; ++dd)
; #pragma unroll
;             for (int e3 = 0; e3 < 3; ++e3) accC[dd][e3] = (f32x4){0.f, 0.f, 0.f, 0.f};
.LBB0_341:
	v_readlane_b32 s83, v255, 63
	s_lshr_b32 s64, s83, 3
	v_readlane_b32 s81, v255, 58
	s_and_b32 s65, s81, 28
	s_and_b32 s64, s64, 7
	s_lshl_b32 s68, s64, 18
	s_lshl_b32 s84, s64, 6
	s_lshl_b32 s85, s64, 2
	s_add_i32 s64, s82, s65
	s_ashr_i32 s65, s64, 31
	s_and_b32 s81, s81, -4
	s_lshr_b32 s86, s83, 6
	s_lshl_b64 s[82:83], s[64:65], 14
	v_mov_b32_e32 v181, s83
	v_or_b32_e32 v180, s82, v144
	s_lshl_b64 s[82:83], s[64:65], 21
	s_add_i32 s81, s81, s86
	s_or_b32 s82, s82, s68
	s_and_b32 s68, s81, 7
	s_lshl_b32 s81, s68, 9
	s_or_b32 s81, s84, s81
	s_or_b32 s52, s52, s81
	s_lshl_b32 s81, s68, 5
	s_lshl_b64 s[54:55], s[54:55], 20
	s_or_b32 s81, s85, s81
	s_or_b32 s54, s54, s81
	v_lshl_add_u64 v[184:185], s[52:53], 0, v[158:159]
	v_lshl_add_u64 v[186:187], s[54:55], 0, v[160:161]
	s_lshl_b64 s[54:55], s[64:65], 20
	v_lshl_add_u64 v[190:191], s[52:53], 0, v[162:163]
	s_lshl_b32 s52, s68, 8
	s_add_u32 s50, s52, s50
	v_mov_b32_e32 v2, v1
	v_mov_b32_e32 v3, v1
	v_readlane_b32 s88, v254, 60
	s_addc_u32 s51, 0, s51
	v_mov_b32_e32 v0, v1
	v_mov_b64_e32 v[78:79], v[2:3]
	v_mov_b64_e32 v[62:63], v[2:3]
	v_mov_b64_e32 v[82:83], v[2:3]
	v_mov_b64_e32 v[66:67], v[2:3]
	v_mov_b64_e32 v[70:71], v[2:3]
	v_mov_b64_e32 v[74:75], v[2:3]
	v_readlane_b32 s89, v254, 61
	v_lshl_add_u64 v[182:183], s[82:83], 0, v[156:157]
	v_lshl_add_u64 v[188:189], v[154:155], 0, s[54:55]
	v_lshl_add_u64 v[192:193], s[50:51], 0, v[164:165]
	s_mov_b32 s52, 0
	v_mov_b64_e32 v[76:77], v[0:1]
	v_mov_b64_e32 v[60:61], v[0:1]
	v_mov_b64_e32 v[80:81], v[0:1]
	v_mov_b64_e32 v[64:65], v[0:1]
	v_mov_b64_e32 v[68:69], v[0:1]
	v_mov_b64_e32 v[72:73], v[0:1]
	s_mov_b32 s81, s91
	s_mov_b32 s91, s90
	s_waitcnt vmcnt(0)
	s_branch .LBB0_343

; #define LAS __attribute__((address_space(3)))
; __device__ __forceinline__ unsigned cvt_pk_bf16(float lo, float hi) { const bf16x2_t r = __builtin_convertvector((f32x2){lo, hi}, bf16x2_t); return __builtin_bit_cast(unsigned, r); }
; __device__ __forceinline__ float bf_lo(unsigned w) { return __uint_as_float(w << 16); }
; __device__ __forceinline__ float bf_hi(unsigned w) { return __uint_as_float(w & 0xffff0000u); }
; #define WG_BARRIER() do { asm volatile("s_waitcnt vmcnt(0) lgkmcnt(0)" ::: "memory"); __builtin_amdgcn_s_barrier(); asm volatile("" ::: "memory"); } while (0)
; #define WG_BARRIER_LDS() do { asm volatile("s_waitcnt lgkmcnt(0)" ::: "memory"); __builtin_amdgcn_s_barrier(); asm volatile("" ::: "memory"); } while (0)
; __device__ __forceinline__ void mlstm_phase(LAS unsigned char* lds, const bf16_t* Q, const bf16_t* Kn, const bf16_t* KT, const bf16_t* VT, const float* LI, const float* LF, bf16_t* HH, const bf16_t* O, float* SS) {
;     ...
;             WG_BARRIER();
;             {
;                 const f32x4 wk0 = *(const LAS f32x4*)(sWk + pseg * 8), wk1 = *(const LAS f32x4*)(sWk + pseg * 8 + 4);
; #pragma unroll
;                 for (int i = 0; i < 4; ++i) { const int row = prow + 32 * i;
;                     *(LAS u32x4*)(lds + L_Q + row * RS + pseg * 16) = rq[i]; *(LAS u32x4*)(lds + L_K + row * RS + pseg * 16) = rk[i];
;                     const u32x4 v = rkt[i]; u32x4 o;
;                     o.x = cvt_pk_bf16(bf_lo(v.x) * wk0[0], bf_hi(v.x) * wk0[1]); o.y = cvt_pk_bf16(bf_lo(v.y) * wk0[2], bf_hi(v.y) * wk0[3]);
;                     o.z = cvt_pk_bf16(bf_lo(v.z) * wk1[0], bf_hi(v.z) * wk1[1]); o.w = cvt_pk_bf16(bf_lo(v.w) * wk1[2], bf_hi(v.w) * wk1[3]);
;                     *(LAS u32x4*)(lds + L_KT + row * RS + pseg * 16) = o; }
;                 *(LAS u32x4*)(lds + L_VT + prow * RS + pseg * 16) = rvt;
;                 *(LAS u32x4*)(lds + L_HS + (tid >> 2) * HS_RS + (tid & 3) * 16) = ro;
;             }
;             WG_BARRIER_LDS();
;             if (c + 1 < NCHUNK) ML_LOAD(c + 1);
.LBB0_343:
	s_and_b32 s53, s52, 1
	s_mul_i32 s50, s53, 0xa40
	s_add_i32 s54, s50, 0
	s_add_i32 s54, s54, 0x23100
	s_waitcnt vmcnt(8) lgkmcnt(0)
	s_barrier
	v_lshl_add_u32 v0, v136, 2, s54
	ds_read_b128 v[84:87], v0 offset:1536
	ds_read_b128 v[88:91], v0 offset:1552
	v_lshlrev_b32_e32 v2, 16, v12
	v_and_b32_e32 v3, 0xffff0000, v12
	ds_write_b128 v210, v[4:7]
	ds_write_b128 v210, v[8:11] offset:34816
	s_waitcnt lgkmcnt(3)
	v_pk_mul_f32 v[2:3], v[84:85], v[2:3]
	s_cmp_eq_u32 s52, 31
	v_cvt_pk_bf16_f32 v92, v2, v3
	v_lshlrev_b32_e32 v2, 16, v13
	v_and_b32_e32 v3, 0xffff0000, v13
	v_pk_mul_f32 v[2:3], v[86:87], v[2:3]
	s_cselect_b64 s[50:51], -1, 0
	v_cvt_pk_bf16_f32 v93, v2, v3
	v_lshlrev_b32_e32 v2, 16, v14
	v_and_b32_e32 v3, 0xffff0000, v14
	s_waitcnt lgkmcnt(2)
	v_pk_mul_f32 v[2:3], v[88:89], v[2:3]
	s_and_b64 vcc, exec, s[50:51]
	v_cvt_pk_bf16_f32 v94, v2, v3
	v_lshlrev_b32_e32 v2, 16, v15
	v_and_b32_e32 v3, 0xffff0000, v15
	v_pk_mul_f32 v[2:3], v[90:91], v[2:3]
	s_nop 0
	v_cvt_pk_bf16_f32 v95, v2, v3
	v_lshlrev_b32_e32 v2, 16, v24
	v_and_b32_e32 v3, 0xffff0000, v24
	v_pk_mul_f32 v[2:3], v[84:85], v[2:3]
	ds_write_b128 v211, v[92:95]
	ds_write_b128 v210, v[16:19] offset:8704
	ds_write_b128 v210, v[20:23] offset:43520
	v_cvt_pk_bf16_f32 v92, v2, v3
	v_lshlrev_b32_e32 v2, 16, v25
	v_and_b32_e32 v3, 0xffff0000, v25
	v_pk_mul_f32 v[2:3], v[86:87], v[2:3]
	s_nop 0
	v_cvt_pk_bf16_f32 v93, v2, v3
	v_lshlrev_b32_e32 v2, 16, v26
	v_and_b32_e32 v3, 0xffff0000, v26
	v_pk_mul_f32 v[2:3], v[88:89], v[2:3]
	s_nop 0
	v_cvt_pk_bf16_f32 v94, v2, v3
	v_lshlrev_b32_e32 v2, 16, v27
	v_and_b32_e32 v3, 0xffff0000, v27
	v_pk_mul_f32 v[2:3], v[90:91], v[2:3]
	s_nop 0
	v_cvt_pk_bf16_f32 v95, v2, v3
	v_lshlrev_b32_e32 v2, 16, v36
	v_and_b32_e32 v3, 0xffff0000, v36
	v_pk_mul_f32 v[2:3], v[84:85], v[2:3]
	ds_write_b128 v211, v[92:95] offset:8704
	ds_write_b128 v210, v[28:31] offset:17408
	ds_write_b128 v210, v[32:35] offset:52224
	v_cvt_pk_bf16_f32 v92, v2, v3
	v_lshlrev_b32_e32 v2, 16, v37
	v_and_b32_e32 v3, 0xffff0000, v37
	v_pk_mul_f32 v[2:3], v[86:87], v[2:3]
	s_nop 0
	v_cvt_pk_bf16_f32 v93, v2, v3
	v_lshlrev_b32_e32 v2, 16, v38
	v_and_b32_e32 v3, 0xffff0000, v38
	v_pk_mul_f32 v[2:3], v[88:89], v[2:3]
	s_nop 0
	v_cvt_pk_bf16_f32 v94, v2, v3
	v_lshlrev_b32_e32 v2, 16, v39
	v_and_b32_e32 v3, 0xffff0000, v39
	v_pk_mul_f32 v[2:3], v[90:91], v[2:3]
	s_nop 0
	v_cvt_pk_bf16_f32 v95, v2, v3
	v_lshlrev_b32_e32 v2, 16, v48
	v_and_b32_e32 v3, 0xffff0000, v48
	v_pk_mul_f32 v[2:3], v[84:85], v[2:3]
	ds_write_b128 v211, v[92:95] offset:17408
	ds_write_b128 v210, v[40:43] offset:26112
	ds_write_b128 v210, v[44:47] offset:60928
	v_cvt_pk_bf16_f32 v84, v2, v3
	v_lshlrev_b32_e32 v2, 16, v49
	v_and_b32_e32 v3, 0xffff0000, v49
	v_pk_mul_f32 v[2:3], v[86:87], v[2:3]
	s_nop 0
	v_cvt_pk_bf16_f32 v85, v2, v3
	v_lshlrev_b32_e32 v2, 16, v50
	v_and_b32_e32 v3, 0xffff0000, v50
	v_pk_mul_f32 v[2:3], v[88:89], v[2:3]
	s_nop 0
	v_cvt_pk_bf16_f32 v86, v2, v3
	v_lshlrev_b32_e32 v2, 16, v51
	v_and_b32_e32 v3, 0xffff0000, v51
	v_pk_mul_f32 v[2:3], v[90:91], v[2:3]
	s_nop 0
	v_cvt_pk_bf16_f32 v87, v2, v3
	ds_write_b128 v211, v[84:87] offset:26112
	ds_write_b128 v212, v[52:55]
	ds_write_b128 v213, v[56:59]
	s_waitcnt lgkmcnt(0)
	s_barrier
	s_cbranch_vccnz .LBB0_345
	v_readlane_b32 s84, v254, 53
	v_readlane_b32 s86, v254, 55
	v_readlane_b32 s87, v254, 56
	v_readlane_b32 s85, v254, 54
	s_nop 0
	v_lshl_add_u64 v[2:3], s[86:87], 0, v[192:193]
	v_add_co_u32_e32 v4, vcc, 0x18540000, v2
	v_lshl_add_u64 v[44:45], s[86:87], 0, v[188:189]
	s_nop 0
	v_addc_co_u32_e32 v5, vcc, 0, v3, vcc
	v_add_co_u32_e32 v8, vcc, 0x1a540000, v2
	v_lshl_add_u64 v[56:57], s[86:87], 0, v[190:191]
	s_nop 0
	v_addc_co_u32_e32 v9, vcc, 0, v3, vcc
	v_add_co_u32_e32 v12, vcc, 0x1c500000, v44
	global_load_dwordx4 v[4:7], v[4:5], off
	s_nop 0
	global_load_dwordx4 v[8:11], v[8:9], off
	v_addc_co_u32_e32 v13, vcc, 0, v45, vcc
	v_add_co_u32_e32 v16, vcc, 0x18550000, v2
	s_nop 1
	v_addc_co_u32_e32 v17, vcc, 0, v3, vcc
	v_add_co_u32_e32 v20, vcc, 0x1a550000, v2
	global_load_dwordx4 v[12:15], v[12:13], off offset:256
	s_nop 0
	global_load_dwordx4 v[16:19], v[16:17], off
	v_addc_co_u32_e32 v21, vcc, 0, v3, vcc
	v_add_co_u32_e32 v24, vcc, 0x1c540000, v44
	s_nop 1
	v_addc_co_u32_e32 v25, vcc, 0, v45, vcc
	v_add_co_u32_e32 v28, vcc, 0x18560000, v2
	global_load_dwordx4 v[20:23], v[20:21], off
	s_nop 0
	global_load_dwordx4 v[24:27], v[24:25], off offset:256
	v_addc_co_u32_e32 v29, vcc, 0, v3, vcc
	v_add_co_u32_e32 v32, vcc, 0x1a560000, v2
	s_nop 1
	v_addc_co_u32_e32 v33, vcc, 0, v3, vcc
	v_add_co_u32_e32 v36, vcc, 0x1c580000, v44
	global_load_dwordx4 v[28:31], v[28:29], off
	s_nop 0
	global_load_dwordx4 v[32:35], v[32:33], off
	v_addc_co_u32_e32 v37, vcc, 0, v45, vcc
	v_add_co_u32_e32 v40, vcc, 0x18570000, v2
	s_nop 1
	v_addc_co_u32_e32 v41, vcc, 0, v3, vcc
	v_add_co_u32_e32 v2, vcc, 0x1a570000, v2
	global_load_dwordx4 v[36:39], v[36:37], off offset:256
	s_nop 0
	global_load_dwordx4 v[40:43], v[40:41], off
	v_addc_co_u32_e32 v3, vcc, 0, v3, vcc
	v_add_co_u32_e32 v48, vcc, 0x1c5c0000, v44
	s_nop 1
	v_addc_co_u32_e32 v49, vcc, 0, v45, vcc
	global_load_dwordx4 v[44:47], v[2:3], off
	s_nop 0
	global_load_dwordx4 v[48:51], v[48:49], off offset:256
	v_lshl_add_u64 v[2:3], s[86:87], 0, v[182:183]
	global_load_dwordx4 v[52:55], v[2:3], off
	s_nop 0
	global_load_dwordx4 v[56:59], v[56:57], off

; #define LAS __attribute__((address_space(3)))
; __device__ __forceinline__ int opaque_tid() { int t = threadIdx.x; asm volatile("" : "+v"(t)); return t; }
; __device__ __forceinline__ void build_head_scale_table(LAS unsigned char* lds, const float* SS, const int round) {
;     const int tid = opaque_tid();
;     if (tid < 256) {
;         const int c = blockIdx.x, pm = 32 * round + 4 * (c & 7) + (c >> 6);
;         const f32x4* sp = (const f32x4*)(SS + ((size_t)pm * 256 + tid) * 64);
;         LAS float* rt = (LAS float*)(lds + L_RT) + tid * 8;
;         float prev = 0.f;
; #pragma unroll 1
;         for (int h = 0; h < 8; ++h) { const f32x4 a = sp[2 * h], b = sp[2 * h + 1];
.LBB0_430:
	s_or_b64 exec, exec, s[0:1]
	s_waitcnt lgkmcnt(0)
	v_mov_b32_e32 v0, v200
	s_movk_i32 s0, 0x100
	s_barrier
	s_ashr_i32 s1, s96, 6
	v_cmp_gt_i32_e32 vcc, s0, v0
	s_lshl_b32 s0, s96, 2
	s_and_b32 s0, s0, 28
	s_add_i32 s90, s0, s1
	s_ashr_i32 s91, s90, 31
	s_and_saveexec_b64 s[2:3], vcc
	s_cbranch_execz .LBB0_436
	s_lshl_b64 s[0:1], s[90:91], 16
	v_ashrrev_i32_e32 v1, 31, v0
	v_lshlrev_b32_e32 v2, 5, v0
	s_add_u32 s0, s78, s0
	s_waitcnt vmcnt(21)
	v_lshlrev_b64 v[4:5], 8, v[0:1]
	v_add_u32_e32 v0, 0, v2
	s_addc_u32 s1, s79, s1
	v_add_u32_e32 v3, 0x1fffc, v0
	v_lshl_add_u64 v[0:1], s[0:1], 0, v[4:5]
	v_mov_b32_e32 v6, 0
	s_mov_b64 s[4:5], 0
	s_mov_b64 s[6:7], 0x644000
	v_mov_b32_e32 v4, 0x358637bd
	s_mov_b32 s10, 0xf800000
	v_mov_b32_e32 v5, 0x260
	s_mov_b32 s11, 0x800000
	v_add_co_u32_e32 v80, vcc, 0x644000, v0
	s_nop 1
	v_addc_co_u32_e32 v81, vcc, 0, v1, vcc
	global_load_dwordx4 v[16:19], v[80:81], off
	global_load_dwordx4 v[20:23], v[80:81], off offset:16
	global_load_dwordx4 v[24:27], v[80:81], off offset:32
	global_load_dwordx4 v[28:31], v[80:81], off offset:48
	global_load_dwordx4 v[32:35], v[80:81], off offset:64
	global_load_dwordx4 v[36:39], v[80:81], off offset:80
	global_load_dwordx4 v[40:43], v[80:81], off offset:96
	global_load_dwordx4 v[44:47], v[80:81], off offset:112
	global_load_dwordx4 v[48:51], v[80:81], off offset:128
	global_load_dwordx4 v[52:55], v[80:81], off offset:144
	global_load_dwordx4 v[56:59], v[80:81], off offset:160
	global_load_dwordx4 v[60:63], v[80:81], off offset:176
	global_load_dwordx4 v[64:67], v[80:81], off offset:192
	global_load_dwordx4 v[68:71], v[80:81], off offset:208
	global_load_dwordx4 v[72:75], v[80:81], off offset:224
	global_load_dwordx4 v[76:79], v[80:81], off offset:240
	s_branch .LBB0_433

; __device__ __forceinline__ void build_head_scale_table(LAS unsigned char* lds, const float* SS, const int round) {
;     ...
;         for (int h = 0; h < 8; ++h) { const f32x4 a = sp[2 * h], b = sp[2 * h + 1];
;             const float ms = (((a[0] + a[1]) + (a[2] + a[3])) + ((b[0] + b[1]) + (b[2] + b[3]))) * (1.0f / DV) + EPS;
;             if (h > 0) rt[h - 1] = prev * sqrtf(ms);
;             prev = rsqrtf(ms); }
;         rt[7] = prev;
.LBB0_433:
	s_waitcnt vmcnt(19)
	v_lshl_add_u64 v[12:13], v[0:1], 0, s[4:5]
	v_add_co_u32_e32 v8, vcc, 0x644000, v12
	s_cmp_eq_u32 s4, 0
	s_nop 0
	v_addc_co_u32_e32 v9, vcc, 0, v13, vcc
	v_lshl_add_u64 v[12:13], v[12:13], 0, s[6:7]
	s_waitcnt vmcnt(0)
	v_mov_b32_e32 v8, v16
	v_mov_b32_e32 v9, v17
	v_mov_b32_e32 v10, v18
	v_mov_b32_e32 v11, v19
	s_nop 0
	v_mov_b32_e32 v12, v20
	v_mov_b32_e32 v13, v21
	v_mov_b32_e32 v14, v22
	v_mov_b32_e32 v15, v23
	v_mov_b32_e32 v16, v24
	v_mov_b32_e32 v17, v25
	v_mov_b32_e32 v18, v26
	v_mov_b32_e32 v19, v27
	v_mov_b32_e32 v20, v28
	v_mov_b32_e32 v21, v29
	v_mov_b32_e32 v22, v30
	v_mov_b32_e32 v23, v31
	v_mov_b32_e32 v24, v32
	v_mov_b32_e32 v25, v33
	v_mov_b32_e32 v26, v34
	v_mov_b32_e32 v27, v35
	v_mov_b32_e32 v28, v36
	v_mov_b32_e32 v29, v37
	v_mov_b32_e32 v30, v38
	v_mov_b32_e32 v31, v39
	v_mov_b32_e32 v32, v40
	v_mov_b32_e32 v33, v41
	v_mov_b32_e32 v34, v42
	v_mov_b32_e32 v35, v43
	v_mov_b32_e32 v36, v44
	v_mov_b32_e32 v37, v45
	v_mov_b32_e32 v38, v46
	v_mov_b32_e32 v39, v47
	v_mov_b32_e32 v40, v48
	v_mov_b32_e32 v41, v49
	v_mov_b32_e32 v42, v50
	v_mov_b32_e32 v43, v51
	v_mov_b32_e32 v44, v52
	v_mov_b32_e32 v45, v53
	v_mov_b32_e32 v46, v54
	v_mov_b32_e32 v47, v55
	v_mov_b32_e32 v48, v56
	v_mov_b32_e32 v49, v57
	v_mov_b32_e32 v50, v58
	v_mov_b32_e32 v51, v59
	v_mov_b32_e32 v52, v60
	v_mov_b32_e32 v53, v61
	v_mov_b32_e32 v54, v62
	v_mov_b32_e32 v55, v63
	v_mov_b32_e32 v56, v64
	v_mov_b32_e32 v57, v65
	v_mov_b32_e32 v58, v66
	v_mov_b32_e32 v59, v67
	v_mov_b32_e32 v60, v68
	v_mov_b32_e32 v61, v69
	v_mov_b32_e32 v62, v70
	v_mov_b32_e32 v63, v71
	v_mov_b32_e32 v64, v72
	v_mov_b32_e32 v65, v73
	v_mov_b32_e32 v66, v74
	v_mov_b32_e32 v67, v75
	v_mov_b32_e32 v68, v76
	v_mov_b32_e32 v69, v77
	v_mov_b32_e32 v70, v78
	v_mov_b32_e32 v71, v79
	s_waitcnt vmcnt(1)
	v_add_f32_e32 v7, v8, v9
	v_add_f32_e32 v8, v10, v11
	s_waitcnt vmcnt(0)
	v_add_f32_e32 v9, v12, v13
	v_add_f32_e32 v10, v14, v15
	v_add_f32_e32 v7, v7, v8
	v_add_f32_e32 v8, v9, v10
	v_add_f32_e32 v7, v7, v8
	v_fmamk_f32 v7, v7, 0x3b800000, v4
	s_cbranch_scc1 .LBB0_432
	v_mul_f32_e32 v8, 0x4f800000, v7
	v_cmp_gt_f32_e32 vcc, s10, v7
	s_nop 1
	v_cndmask_b32_e32 v8, v7, v8, vcc
	v_sqrt_f32_e32 v9, v8
	s_nop 0
	v_add_u32_e32 v10, -1, v9
	v_fma_f32 v12, -v10, v9, v8
	v_add_u32_e32 v11, 1, v9
	v_cmp_ge_f32_e64 s[0:1], 0, v12
	s_nop 1
	v_cndmask_b32_e64 v10, v9, v10, s[0:1]
	v_fma_f32 v9, -v11, v9, v8
	v_cmp_lt_f32_e64 s[0:1], 0, v9
	s_nop 1
	v_cndmask_b32_e64 v9, v10, v11, s[0:1]
	v_mul_f32_e32 v10, 0x37800000, v9
	v_cndmask_b32_e32 v9, v9, v10, vcc
	v_cmp_class_f32_e32 vcc, v8, v5
	s_nop 1
	v_cndmask_b32_e32 v8, v9, v8, vcc
	v_mul_f32_e32 v6, v6, v8
	ds_write_b32 v3, v6
	s_branch .LBB0_432

; __device__ __forceinline__ unsigned cvt_pk_bf16(float lo, float hi) { const bf16x2_t r = __builtin_convertvector((f32x2){lo, hi}, bf16x2_t); return __builtin_bit_cast(unsigned, r); }
;     __device__ __forceinline__ void fused(AccT& acc, const Unit& u, int wr, int wc, int fr, int fq, LAS unsigned char* lds) const {
;     ...
;         f32x4 c0[2][2], c1[2][2];
; #pragma unroll
;         for (int bj = 0; bj < 2; ++bj)
; #pragma unroll
;             for (int n = 0; n < 2; ++n) { const int col = col0 + bj * HALF + n * 4;
;                 if (FINAL) { c0[bj][n] = *(const f32x4*)(fg + col); c1[bj][n] = (f32x4){0.f, 0.f, 0.f, 0.f}; }
;                 else { c0[bj][n] = *(const f32x4*)(modn + bb * 6144 + DM + col) + 1.0f; c1[bj][n] = *(const f32x4*)(modn + bb * 6144 + col); } }
; #pragma unroll
;         for (int ai = 0; ai < 2; ++ai)
; #pragma unroll
;             for (int m = 0; m < 4; ++m) { const int rl = ai * HALF + wr * 64 + m * 16 + fr; const float rstd = Ssh[rl]; const size_t off = (size_t)(row0 + ai * HALF + m * 16) * DM + col0;
; #pragma unroll
;                 for (int bj = 0; bj < 2; ++bj) { const f32x4 o0 = acc[ai][bj][m][0] * rstd * c0[bj][0] + c1[bj][0], o1 = acc[ai][bj][m][1] * rstd * c0[bj][1] + c1[bj][1];
;                     if (FINAL) { *(f32x4*)(OUT + off + bj * HALF) = o0; *(f32x4*)(OUT + off + bj * HALF + 4) = o1; }
;                     else { u32x4 w; w.x = cvt_pk_bf16(o0[0], o0[1]); w.y = cvt_pk_bf16(o0[2], o0[3]); w.z = cvt_pk_bf16(o1[0], o1[1]); w.w = cvt_pk_bf16(o1[2], o1[3]);
;                         *(u32x4*)(H + off + bj * HALF) = w; } } }
.LBB0_477:
	s_or_b64 exec, exec, s[10:11]
	s_add_u32 s36, s78, 0x18000
	s_addc_u32 s37, s79, 0
	s_add_u32 s38, s78, 0x28500000
	s_addc_u32 s39, s79, 0
	s_add_u32 s0, s36, s8
	s_addc_u32 s1, s37, s9
	s_add_u32 s10, s0, 0x2000
	s_waitcnt vmcnt(0) lgkmcnt(0)
	s_barrier
	s_addc_u32 s11, s1, 0
	global_load_dwordx4 v[168:171], v146, s[10:11]
	global_load_dwordx4 v[172:175], v146, s[10:11] offset:16
	v_or_b32_e32 v0, 0x200, v146
	global_load_dwordx4 v[176:179], v0, s[10:11]
	global_load_dwordx4 v[180:183], v0, s[10:11] offset:16
	global_load_dwordx4 v[12:15], v146, s[0:1]
	global_load_dwordx4 v[8:11], v146, s[0:1] offset:16
	global_load_dwordx4 v[4:7], v146, s[0:1] offset:512
	s_waitcnt lgkmcnt(0)
	global_load_dwordx4 v[0:3], v146, s[0:1] offset:528
	s_lshl_b32 s0, s20, 2
	s_add_i32 s0, s0, 0
	v_lshl_add_u32 v148, v166, 2, s0
	v_add_u32_e32 v198, 0x2000, v148
	ds_read2_b32 v[148:149], v198 offset1:16
	ds_read2_b32 v[166:167], v198 offset0:32 offset1:48
	v_mov_b32_e32 v145, 0
	v_lshl_add_u64 v[146:147], s[38:39], 0, v[152:153]
	v_lshl_add_u64 v[152:153], v[146:147], 0, v[144:145]
	s_waitcnt lgkmcnt(1)
	v_pk_mul_f32 v[146:147], v[148:149], v[70:71] op_sel_hi:[0,1]
	v_mov_b32_e32 v70, v149
	v_pk_mul_f32 v[194:195], v[148:149], v[100:101] op_sel_hi:[0,1]
	v_pk_mul_f32 v[104:105], v[70:71], v[104:105] op_sel_hi:[0,1]
	v_pk_mul_f32 v[186:187], v[148:149], v[78:79] op_sel_hi:[0,1]
	v_pk_mul_f32 v[190:191], v[148:149], v[86:87] op_sel_hi:[0,1]
	v_pk_mul_f32 v[192:193], v[148:149], v[94:95] op_sel_hi:[0,1]
	v_pk_mul_f32 v[118:119], v[70:71], v[118:119] op_sel_hi:[0,1]
	s_waitcnt lgkmcnt(0)
	v_pk_mul_f32 v[98:99], v[166:167], v[98:99] op_sel_hi:[0,1]
	v_pk_mul_f32 v[88:89], v[166:167], v[88:89] op_sel_hi:[0,1]
	v_pk_mul_f32 v[184:185], v[148:149], v[76:77] op_sel_hi:[0,1]
	v_pk_mul_f32 v[188:189], v[148:149], v[84:85] op_sel_hi:[0,1]
	v_pk_mul_f32 v[196:197], v[148:149], v[102:103] op_sel_hi:[0,1]
	v_pk_mul_f32 v[96:97], v[166:167], v[96:97] op_sel_hi:[0,1]
	v_pk_mul_f32 v[110:111], v[70:71], v[110:111] op_sel_hi:[0,1]
	v_pk_mul_f32 v[112:113], v[70:71], v[112:113] op_sel_hi:[0,1]
	v_pk_mul_f32 v[114:115], v[70:71], v[114:115] op_sel_hi:[0,1]
	v_pk_mul_f32 v[116:117], v[70:71], v[116:117] op_sel_hi:[0,1]
	v_pk_mul_f32 v[120:121], v[70:71], v[120:121] op_sel_hi:[0,1]
	v_pk_mul_f32 v[122:123], v[70:71], v[122:123] op_sel_hi:[0,1]
	v_lshl_add_u64 v[150:151], s[38:39], 0, v[150:151]
	v_pk_mul_f32 v[36:37], v[166:167], v[36:37] op_sel_hi:[0,1]
	v_pk_mul_f32 v[30:31], v[166:167], v[30:31] op_sel_hi:[0,1]
	v_pk_mul_f32 v[22:23], v[166:167], v[22:23] op_sel_hi:[0,1]
	v_pk_mul_f32 v[20:21], v[166:167], v[20:21] op_sel_hi:[0,1]
	v_lshl_add_u64 v[150:151], v[150:151], 0, v[144:145]
	s_movk_i32 s0, 0x100
	s_add_i32 s92, s90, 32
	s_ashr_i32 s93, s92, 31
	s_waitcnt vmcnt(5)
	v_pk_add_f32 v[78:79], v[178:179], 1.0 op_sel_hi:[1,0]
	v_pk_add_f32 v[84:85], v[176:177], 1.0 op_sel_hi:[1,0]
	v_pk_add_f32 v[100:101], v[170:171], 1.0 op_sel_hi:[1,0]
	v_pk_add_f32 v[86:87], v[174:175], 1.0 op_sel_hi:[1,0]
	v_pk_add_f32 v[94:95], v[172:173], 1.0 op_sel_hi:[1,0]
	s_waitcnt vmcnt(3)
	v_pk_fma_f32 v[104:105], v[100:101], v[104:105], v[14:15]
	v_pk_add_f32 v[102:103], v[168:169], 1.0 op_sel_hi:[1,0]
	s_waitcnt vmcnt(2)
	v_pk_fma_f32 v[170:171], v[94:95], v[186:187], v[8:9]
	s_waitcnt vmcnt(1)
	v_pk_fma_f32 v[186:187], v[78:79], v[118:119], v[6:7]
	v_cvt_pk_bf16_f32 v119, v104, v105
	v_pk_mul_f32 v[104:105], v[166:167], v[106:107] op_sel_hi:[0,1]
	v_pk_fma_f32 v[98:99], v[100:101], v[98:99], v[14:15]
	v_pk_fma_f32 v[88:89], v[86:87], v[88:89], v[10:11]
	v_pk_add_f32 v[70:71], v[182:183], 1.0 op_sel_hi:[1,0]
	v_pk_add_f32 v[76:77], v[180:181], 1.0 op_sel_hi:[1,0]
	v_pk_fma_f32 v[148:149], v[100:101], v[184:185], v[14:15]
	v_pk_fma_f32 v[146:147], v[102:103], v[146:147], v[12:13]
	v_pk_fma_f32 v[168:169], v[86:87], v[188:189], v[10:11]
	v_pk_fma_f32 v[104:105], v[102:103], v[104:105], v[12:13]
	v_pk_fma_f32 v[106:107], v[94:95], v[96:97], v[8:9]
	v_cvt_pk_bf16_f32 v97, v98, v99
	v_cvt_pk_bf16_f32 v99, v88, v89
	v_lshl_add_u64 v[88:89], s[38:39], 0, v[108:109]
	v_pk_fma_f32 v[172:173], v[78:79], v[192:193], v[6:7]
	v_pk_fma_f32 v[174:175], v[84:85], v[190:191], v[4:5]
	s_waitcnt vmcnt(0)
	v_pk_fma_f32 v[176:177], v[70:71], v[196:197], v[2:3]
	v_pk_fma_f32 v[178:179], v[76:77], v[194:195], v[0:1]
	v_pk_fma_f32 v[180:181], v[102:103], v[110:111], v[12:13]
	v_pk_fma_f32 v[182:183], v[86:87], v[114:115], v[10:11]
	v_pk_fma_f32 v[184:185], v[94:95], v[112:113], v[8:9]
	v_pk_fma_f32 v[188:189], v[84:85], v[116:117], v[4:5]
	v_pk_fma_f32 v[122:123], v[70:71], v[122:123], v[2:3]
	v_pk_fma_f32 v[190:191], v[76:77], v[120:121], v[0:1]
	v_cvt_pk_bf16_f32 v110, v146, v147
	v_cvt_pk_bf16_f32 v111, v148, v149
	v_cvt_pk_bf16_f32 v112, v170, v171
	v_cvt_pk_bf16_f32 v113, v168, v169
	v_cvt_pk_bf16_f32 v96, v104, v105
	v_cvt_pk_bf16_f32 v98, v106, v107
	v_lshl_add_u64 v[88:89], v[88:89], 0, v[144:145]
	v_cvt_pk_bf16_f32 v114, v174, v175
	v_cvt_pk_bf16_f32 v115, v172, v173
	v_cvt_pk_bf16_f32 v116, v178, v179
	v_cvt_pk_bf16_f32 v117, v176, v177
	v_cvt_pk_bf16_f32 v118, v180, v181
	v_cvt_pk_bf16_f32 v120, v184, v185
	v_cvt_pk_bf16_f32 v121, v182, v183
	v_cvt_pk_bf16_f32 v146, v188, v189
	v_cvt_pk_bf16_f32 v147, v186, v187
	v_cvt_pk_bf16_f32 v148, v190, v191
	v_cvt_pk_bf16_f32 v149, v122, v123
	global_store_dwordx4 v[152:153], v[110:113], off
	global_store_dwordx4 v[152:153], v[114:117], off offset:256
	global_store_dwordx4 v[150:151], v[118:121], off
	global_store_dwordx4 v[150:151], v[146:149], off offset:256
	global_store_dwordx4 v[88:89], v[96:99], off
	v_pk_fma_f32 v[30:31], v[78:79], v[30:31], v[6:7]
; __device__ __forceinline__ unsigned cvt_pk_bf16(float lo, float hi) { const bf16x2_t r = __builtin_convertvector((f32x2){lo, hi}, bf16x2_t); return __builtin_bit_cast(unsigned, r); }
;     __device__ __forceinline__ void fused(AccT& acc, const Unit& u, int wr, int wc, int fr, int fq, LAS unsigned char* lds) const {
;     ...
; #pragma unroll
;         for (int ai = 0; ai < 2; ++ai)
; #pragma unroll
;             for (int m = 0; m < 4; ++m) { const int rl = ai * HALF + wr * 64 + m * 16 + fr; const float rstd = Ssh[rl]; const size_t off = (size_t)(row0 + ai * HALF + m * 16) * DM + col0;
; #pragma unroll
;                 for (int bj = 0; bj < 2; ++bj) { const f32x4 o0 = acc[ai][bj][m][0] * rstd * c0[bj][0] + c1[bj][0], o1 = acc[ai][bj][m][1] * rstd * c0[bj][1] + c1[bj][1];
;                     if (FINAL) { *(f32x4*)(OUT + off + bj * HALF) = o0; *(f32x4*)(OUT + off + bj * HALF + 4) = o1; }
;                     else { u32x4 w; w.x = cvt_pk_bf16(o0[0], o0[1]); w.y = cvt_pk_bf16(o0[2], o0[3]); w.z = cvt_pk_bf16(o1[0], o1[1]); w.w = cvt_pk_bf16(o1[2], o1[3]);
;                         *(u32x4*)(H + off + bj * HALF) = w; } } }
	v_pk_fma_f32 v[36:37], v[84:85], v[36:37], v[4:5]
	v_pk_fma_f32 v[96:97], v[70:71], v[20:21], v[2:3]
	v_pk_fma_f32 v[22:23], v[76:77], v[22:23], v[0:1]
	v_cvt_pk_bf16_f32 v20, v36, v37
	v_cvt_pk_bf16_f32 v21, v30, v31
	v_cvt_pk_bf16_f32 v22, v22, v23
	v_cvt_pk_bf16_f32 v23, v96, v97
	v_mov_b32_e32 v30, v167
	global_store_dwordx4 v[88:89], v[20:23], off offset:256
	v_pk_mul_f32 v[36:37], v[30:31], v[90:91] op_sel_hi:[0,1]
	v_pk_mul_f32 v[80:81], v[30:31], v[80:81] op_sel_hi:[0,1]
	v_pk_mul_f32 v[20:21], v[30:31], v[130:131] op_sel_hi:[0,1]
	v_pk_mul_f32 v[22:23], v[30:31], v[126:127] op_sel_hi:[0,1]
	v_pk_fma_f32 v[22:23], v[100:101], v[22:23], v[14:15]
	v_pk_fma_f32 v[20:21], v[102:103], v[20:21], v[12:13]
	v_pk_fma_f32 v[36:37], v[94:95], v[36:37], v[8:9]
	v_pk_fma_f32 v[80:81], v[86:87], v[80:81], v[10:11]
	v_cvt_pk_bf16_f32 v20, v20, v21
	v_cvt_pk_bf16_f32 v21, v22, v23
	v_cvt_pk_bf16_f32 v22, v36, v37
	v_lshl_add_u64 v[36:37], s[38:39], 0, v[92:93]
	v_cvt_pk_bf16_f32 v23, v80, v81
	v_lshl_add_u64 v[36:37], v[36:37], 0, v[144:145]
	v_pk_mul_f32 v[52:53], v[30:31], v[52:53] op_sel_hi:[0,1]
	global_store_dwordx4 v[36:37], v[20:23], off
	s_nop 1
	v_pk_mul_f32 v[20:21], v[30:31], v[72:73] op_sel_hi:[0,1]
	v_pk_mul_f32 v[22:23], v[30:31], v[62:63] op_sel_hi:[0,1]
	v_pk_mul_f32 v[30:31], v[30:31], v[46:47] op_sel_hi:[0,1]
	v_pk_fma_f32 v[46:47], v[76:77], v[52:53], v[0:1]
	ds_read2_b32 v[52:53], v198 offset0:128 offset1:144
	v_pk_fma_f32 v[22:23], v[78:79], v[22:23], v[6:7]
	v_pk_fma_f32 v[20:21], v[84:85], v[20:21], v[4:5]
	v_pk_fma_f32 v[30:31], v[70:71], v[30:31], v[2:3]
	v_cvt_pk_bf16_f32 v20, v20, v21
	v_cvt_pk_bf16_f32 v21, v22, v23
	v_cvt_pk_bf16_f32 v22, v46, v47
	v_cvt_pk_bf16_f32 v23, v30, v31
	global_store_dwordx4 v[36:37], v[20:23], off offset:256
	s_waitcnt lgkmcnt(0)
	v_pk_mul_f32 v[30:31], v[52:53], v[82:83] op_sel_hi:[0,1]
	v_pk_mul_f32 v[36:37], v[52:53], v[74:75] op_sel_hi:[0,1]
	v_pk_mul_f32 v[20:21], v[52:53], v[128:129] op_sel_hi:[0,1]
	v_pk_mul_f32 v[22:23], v[52:53], v[124:125] op_sel_hi:[0,1]
	v_pk_fma_f32 v[22:23], v[100:101], v[22:23], v[14:15]
	v_pk_fma_f32 v[20:21], v[102:103], v[20:21], v[12:13]
	v_pk_fma_f32 v[30:31], v[94:95], v[30:31], v[8:9]
	v_pk_fma_f32 v[36:37], v[86:87], v[36:37], v[10:11]
	v_cvt_pk_bf16_f32 v20, v20, v21
	v_cvt_pk_bf16_f32 v21, v22, v23
	v_cvt_pk_bf16_f32 v22, v30, v31
	v_lshl_add_u64 v[30:31], s[38:39], 0, v[68:69]
	v_cvt_pk_bf16_f32 v23, v36, v37
	v_lshl_add_u64 v[30:31], v[30:31], 0, v[144:145]
	global_store_dwordx4 v[30:31], v[20:23], off
	v_pk_mul_f32 v[36:37], v[52:53], v[48:49] op_sel_hi:[0,1]
	v_pk_mul_f32 v[38:39], v[52:53], v[38:39] op_sel_hi:[0,1]
	v_pk_mul_f32 v[20:21], v[52:53], v[56:57] op_sel_hi:[0,1]
	v_pk_mul_f32 v[22:23], v[52:53], v[54:55] op_sel_hi:[0,1]
	v_pk_fma_f32 v[22:23], v[78:79], v[22:23], v[6:7]
	v_pk_fma_f32 v[20:21], v[84:85], v[20:21], v[4:5]
	v_pk_fma_f32 v[38:39], v[70:71], v[38:39], v[2:3]
	v_pk_fma_f32 v[36:37], v[76:77], v[36:37], v[0:1]
	v_cvt_pk_bf16_f32 v20, v20, v21
	v_cvt_pk_bf16_f32 v21, v22, v23
	v_cvt_pk_bf16_f32 v22, v36, v37
	v_cvt_pk_bf16_f32 v23, v38, v39
	global_store_dwordx4 v[30:31], v[20:23], off offset:256
	v_mov_b32_e32 v30, v53
	v_pk_mul_f32 v[36:37], v[30:31], v[138:139] op_sel_hi:[0,1]
	v_pk_mul_f32 v[20:21], v[30:31], v[156:157] op_sel_hi:[0,1]
	v_pk_mul_f32 v[22:23], v[30:31], v[142:143] op_sel_hi:[0,1]
	v_pk_fma_f32 v[22:23], v[100:101], v[22:23], v[14:15]
	v_pk_fma_f32 v[20:21], v[102:103], v[20:21], v[12:13]
	v_pk_mul_f32 v[38:39], v[30:31], v[134:135] op_sel_hi:[0,1]
	v_pk_fma_f32 v[36:37], v[94:95], v[36:37], v[8:9]
	v_pk_fma_f32 v[38:39], v[86:87], v[38:39], v[10:11]
	v_cvt_pk_bf16_f32 v20, v20, v21
	v_cvt_pk_bf16_f32 v21, v22, v23
	v_cvt_pk_bf16_f32 v22, v36, v37
	v_lshl_add_u64 v[36:37], s[38:39], 0, v[60:61]
	v_cvt_pk_bf16_f32 v23, v38, v39
	v_lshl_add_u64 v[36:37], v[36:37], 0, v[144:145]
	v_pk_mul_f32 v[38:39], v[30:31], v[40:41] op_sel_hi:[0,1]
	global_store_dwordx4 v[36:37], v[20:23], off
	s_nop 1
	v_pk_mul_f32 v[20:21], v[30:31], v[50:51] op_sel_hi:[0,1]
	v_pk_mul_f32 v[22:23], v[30:31], v[42:43] op_sel_hi:[0,1]
	v_pk_mul_f32 v[30:31], v[30:31], v[32:33] op_sel_hi:[0,1]
	v_pk_fma_f32 v[32:33], v[76:77], v[38:39], v[0:1]
	ds_read2_b32 v[38:39], v198 offset0:160 offset1:176
	v_pk_fma_f32 v[22:23], v[78:79], v[22:23], v[6:7]
	v_pk_fma_f32 v[20:21], v[84:85], v[20:21], v[4:5]
	v_pk_fma_f32 v[30:31], v[70:71], v[30:31], v[2:3]
	v_cvt_pk_bf16_f32 v20, v20, v21
	v_cvt_pk_bf16_f32 v21, v22, v23
	v_cvt_pk_bf16_f32 v22, v32, v33
	v_cvt_pk_bf16_f32 v23, v30, v31
	global_store_dwordx4 v[36:37], v[20:23], off offset:256
	s_waitcnt lgkmcnt(0)
; #define LAS __attribute__((address_space(3)))
; __device__ __forceinline__ unsigned cvt_pk_bf16(float lo, float hi) { const bf16x2_t r = __builtin_convertvector((f32x2){lo, hi}, bf16x2_t); return __builtin_bit_cast(unsigned, r); }
; __device__ __forceinline__ int opaque_tid() { int t = threadIdx.x; asm volatile("" : "+v"(t)); return t; }
; #define WG_BARRIER_LDS() do { asm volatile("s_waitcnt lgkmcnt(0)" ::: "memory"); __builtin_amdgcn_s_barrier(); asm volatile("" ::: "memory"); } while (0)
;     __device__ __forceinline__ void fused(AccT& acc, const Unit& u, int wr, int wc, int fr, int fq, LAS unsigned char* lds) const {
;     ...
;         for (int ai = 0; ai < 2; ++ai)
; #pragma unroll
;             for (int m = 0; m < 4; ++m) { const int rl = ai * HALF + wr * 64 + m * 16 + fr; const float rstd = Ssh[rl]; const size_t off = (size_t)(row0 + ai * HALF + m * 16) * DM + col0;
; #pragma unroll
;                 for (int bj = 0; bj < 2; ++bj) { const f32x4 o0 = acc[ai][bj][m][0] * rstd * c0[bj][0] + c1[bj][0], o1 = acc[ai][bj][m][1] * rstd * c0[bj][1] + c1[bj][1];
;                     if (FINAL) { *(f32x4*)(OUT + off + bj * HALF) = o0; *(f32x4*)(OUT + off + bj * HALF + 4) = o1; }
;                     else { u32x4 w; w.x = cvt_pk_bf16(o0[0], o0[1]); w.y = cvt_pk_bf16(o0[2], o0[3]); w.z = cvt_pk_bf16(o1[0], o1[1]); w.w = cvt_pk_bf16(o1[2], o1[3]);
;                         *(u32x4*)(H + off + bj * HALF) = w; } } }
;         WG_BARRIER_LDS();
; __device__ __forceinline__ void build_head_scale_table(LAS unsigned char* lds, const float* SS, const int round) {
;     const int tid = opaque_tid();
;     if (tid < 256) {
;         const int c = blockIdx.x, pm = 32 * round + 4 * (c & 7) + (c >> 6);
;         const f32x4* sp = (const f32x4*)(SS + ((size_t)pm * 256 + tid) * 64);
;         LAS float* rt = (LAS float*)(lds + L_RT) + tid * 8;
;         float prev = 0.f;
; #pragma unroll 1
;         for (int h = 0; h < 8; ++h) { const f32x4 a = sp[2 * h], b = sp[2 * h + 1];
	v_pk_mul_f32 v[30:31], v[38:39], v[136:137] op_sel_hi:[0,1]
	v_pk_mul_f32 v[32:33], v[38:39], v[132:133] op_sel_hi:[0,1]
	v_pk_mul_f32 v[20:21], v[38:39], v[154:155] op_sel_hi:[0,1]
	v_pk_mul_f32 v[22:23], v[38:39], v[140:141] op_sel_hi:[0,1]
	v_pk_fma_f32 v[22:23], v[100:101], v[22:23], v[14:15]
	v_pk_fma_f32 v[20:21], v[102:103], v[20:21], v[12:13]
	v_pk_fma_f32 v[30:31], v[94:95], v[30:31], v[8:9]
	v_pk_fma_f32 v[32:33], v[86:87], v[32:33], v[10:11]
	v_cvt_pk_bf16_f32 v20, v20, v21
	v_cvt_pk_bf16_f32 v21, v22, v23
	v_cvt_pk_bf16_f32 v22, v30, v31
	v_lshl_add_u64 v[30:31], s[38:39], 0, v[44:45]
	v_cvt_pk_bf16_f32 v23, v32, v33
	v_lshl_add_u64 v[30:31], v[30:31], 0, v[144:145]
	global_store_dwordx4 v[30:31], v[20:23], off
	v_pk_mul_f32 v[24:25], v[38:39], v[24:25] op_sel_hi:[0,1]
	v_pk_mul_f32 v[16:17], v[38:39], v[16:17] op_sel_hi:[0,1]
	v_pk_mul_f32 v[20:21], v[38:39], v[34:35] op_sel_hi:[0,1]
	v_pk_mul_f32 v[22:23], v[38:39], v[26:27] op_sel_hi:[0,1]
	v_pk_fma_f32 v[22:23], v[78:79], v[22:23], v[6:7]
	v_pk_fma_f32 v[20:21], v[84:85], v[20:21], v[4:5]
	v_pk_fma_f32 v[16:17], v[70:71], v[16:17], v[2:3]
	v_pk_fma_f32 v[24:25], v[76:77], v[24:25], v[0:1]
	v_cvt_pk_bf16_f32 v20, v20, v21
	v_cvt_pk_bf16_f32 v21, v22, v23
	v_cvt_pk_bf16_f32 v22, v24, v25
	v_cvt_pk_bf16_f32 v23, v16, v17
	v_mov_b32_e32 v16, v39
	global_store_dwordx4 v[30:31], v[20:23], off offset:256
	s_nop 1
	v_pk_mul_f32 v[20:21], v[16:17], v[164:165] op_sel_hi:[0,1]
	v_pk_mul_f32 v[22:23], v[16:17], v[162:163] op_sel_hi:[0,1]
	v_pk_fma_f32 v[14:15], v[100:101], v[22:23], v[14:15]
	v_pk_fma_f32 v[12:13], v[102:103], v[20:21], v[12:13]
	v_pk_mul_f32 v[20:21], v[16:17], v[160:161] op_sel_hi:[0,1]
	v_pk_mul_f32 v[22:23], v[16:17], v[158:159] op_sel_hi:[0,1]
	v_pk_fma_f32 v[22:23], v[86:87], v[22:23], v[10:11]
	v_pk_fma_f32 v[10:11], v[94:95], v[20:21], v[8:9]
	v_cvt_pk_bf16_f32 v8, v12, v13
	v_lshl_add_u64 v[12:13], s[38:39], 0, v[28:29]
	v_cvt_pk_bf16_f32 v9, v14, v15
	v_cvt_pk_bf16_f32 v10, v10, v11
	v_cvt_pk_bf16_f32 v11, v22, v23
	v_lshl_add_u64 v[12:13], v[12:13], 0, v[144:145]
	global_store_dwordx4 v[12:13], v[8:11], off
	s_nop 1
	v_pk_mul_f32 v[8:9], v[16:17], v[66:67] op_sel_hi:[0,1]
	v_pk_mul_f32 v[10:11], v[16:17], v[64:65] op_sel_hi:[0,1]
	v_pk_fma_f32 v[6:7], v[78:79], v[10:11], v[6:7]
	v_pk_fma_f32 v[4:5], v[84:85], v[8:9], v[4:5]
	v_pk_mul_f32 v[8:9], v[16:17], v[58:59] op_sel_hi:[0,1]
	v_pk_mul_f32 v[10:11], v[16:17], v[18:19] op_sel_hi:[0,1]
	v_pk_fma_f32 v[10:11], v[70:71], v[10:11], v[2:3]
	v_pk_fma_f32 v[2:3], v[76:77], v[8:9], v[0:1]
	v_cvt_pk_bf16_f32 v0, v4, v5
	v_cvt_pk_bf16_f32 v1, v6, v7
	v_cvt_pk_bf16_f32 v2, v2, v3
	v_cvt_pk_bf16_f32 v3, v10, v11
	global_store_dwordx4 v[12:13], v[0:3], off offset:256
	s_waitcnt lgkmcnt(0)
	s_barrier
	s_nop 0
	v_mov_b32_e32 v0, v200
	s_nop 0
	v_cmp_gt_i32_e32 vcc, s0, v0
	s_and_saveexec_b64 s[14:15], vcc
	s_cbranch_execz .LBB0_483
	s_lshl_b64 s[0:1], s[92:93], 16
	v_ashrrev_i32_e32 v1, 31, v0
	v_lshlrev_b32_e32 v2, 5, v0
	s_add_u32 s0, s78, s0
	v_lshlrev_b64 v[4:5], 8, v[0:1]
	v_add_u32_e32 v0, 0, v2
	s_addc_u32 s1, s79, s1
	v_add_u32_e32 v3, 0x1fffc, v0
	v_lshl_add_u64 v[0:1], s[0:1], 0, v[4:5]
	s_mov_b64 s[18:19], 0
	s_mov_b64 s[20:21], 0x644000
	v_mov_b32_e32 v4, 0x358637bd
	s_mov_b32 s24, 0xf800000
	v_mov_b32_e32 v5, 0x260
	s_mov_b32 s25, 0x800000
	v_add_co_u32_e32 v80, vcc, 0x644000, v0
	s_nop 1
	v_addc_co_u32_e32 v81, vcc, 0, v1, vcc
	global_load_dwordx4 v[16:19], v[80:81], off
	global_load_dwordx4 v[20:23], v[80:81], off offset:16
	global_load_dwordx4 v[24:27], v[80:81], off offset:32
	global_load_dwordx4 v[28:31], v[80:81], off offset:48
	global_load_dwordx4 v[32:35], v[80:81], off offset:64
	global_load_dwordx4 v[36:39], v[80:81], off offset:80
	global_load_dwordx4 v[40:43], v[80:81], off offset:96
	global_load_dwordx4 v[44:47], v[80:81], off offset:112
	global_load_dwordx4 v[48:51], v[80:81], off offset:128
	global_load_dwordx4 v[52:55], v[80:81], off offset:144
	global_load_dwordx4 v[56:59], v[80:81], off offset:160
	global_load_dwordx4 v[60:63], v[80:81], off offset:176
	global_load_dwordx4 v[64:67], v[80:81], off offset:192
	global_load_dwordx4 v[68:71], v[80:81], off offset:208
	global_load_dwordx4 v[72:75], v[80:81], off offset:224
	global_load_dwordx4 v[76:79], v[80:81], off offset:240
	s_branch .LBB0_480

; __device__ __forceinline__ void build_head_scale_table(LAS unsigned char* lds, const float* SS, const int round) {
;     ...
;         for (int h = 0; h < 8; ++h) { const f32x4 a = sp[2 * h], b = sp[2 * h + 1];
;             const float ms = (((a[0] + a[1]) + (a[2] + a[3])) + ((b[0] + b[1]) + (b[2] + b[3]))) * (1.0f / DV) + EPS;
;             if (h > 0) rt[h - 1] = prev * sqrtf(ms);
;             prev = rsqrtf(ms); }
;         rt[7] = prev;
.LBB0_480:
	v_lshl_add_u64 v[10:11], v[0:1], 0, s[18:19]
	v_add_co_u32_e32 v6, vcc, 0x644000, v10
	s_cmp_eq_u32 s18, 0
	s_nop 0
	v_addc_co_u32_e32 v7, vcc, 0, v11, vcc
	v_lshl_add_u64 v[10:11], v[10:11], 0, s[20:21]
	s_waitcnt vmcnt(0)
	v_mov_b32_e32 v6, v16
	v_mov_b32_e32 v7, v17
	v_mov_b32_e32 v8, v18
	v_mov_b32_e32 v9, v19
	s_nop 0
	v_mov_b32_e32 v10, v20
	v_mov_b32_e32 v11, v21
	v_mov_b32_e32 v12, v22
	v_mov_b32_e32 v13, v23
	v_mov_b32_e32 v16, v24
	v_mov_b32_e32 v17, v25
	v_mov_b32_e32 v18, v26
	v_mov_b32_e32 v19, v27
	v_mov_b32_e32 v20, v28
	v_mov_b32_e32 v21, v29
	v_mov_b32_e32 v22, v30
	v_mov_b32_e32 v23, v31
	v_mov_b32_e32 v24, v32
	v_mov_b32_e32 v25, v33
	v_mov_b32_e32 v26, v34
	v_mov_b32_e32 v27, v35
	v_mov_b32_e32 v28, v36
	v_mov_b32_e32 v29, v37
	v_mov_b32_e32 v30, v38
	v_mov_b32_e32 v31, v39
	v_mov_b32_e32 v32, v40
	v_mov_b32_e32 v33, v41
	v_mov_b32_e32 v34, v42
	v_mov_b32_e32 v35, v43
	v_mov_b32_e32 v36, v44
	v_mov_b32_e32 v37, v45
	v_mov_b32_e32 v38, v46
	v_mov_b32_e32 v39, v47
	v_mov_b32_e32 v40, v48
	v_mov_b32_e32 v41, v49
	v_mov_b32_e32 v42, v50
	v_mov_b32_e32 v43, v51
	v_mov_b32_e32 v44, v52
	v_mov_b32_e32 v45, v53
	v_mov_b32_e32 v46, v54
	v_mov_b32_e32 v47, v55
	v_mov_b32_e32 v48, v56
	v_mov_b32_e32 v49, v57
	v_mov_b32_e32 v50, v58
	v_mov_b32_e32 v51, v59
	v_mov_b32_e32 v52, v60
	v_mov_b32_e32 v53, v61
	v_mov_b32_e32 v54, v62
	v_mov_b32_e32 v55, v63
	v_mov_b32_e32 v56, v64
	v_mov_b32_e32 v57, v65
	v_mov_b32_e32 v58, v66
	v_mov_b32_e32 v59, v67
	v_mov_b32_e32 v60, v68
	v_mov_b32_e32 v61, v69
	v_mov_b32_e32 v62, v70
	v_mov_b32_e32 v63, v71
	v_mov_b32_e32 v64, v72
	v_mov_b32_e32 v65, v73
	v_mov_b32_e32 v66, v74
	v_mov_b32_e32 v67, v75
	v_mov_b32_e32 v68, v76
	v_mov_b32_e32 v69, v77
	v_mov_b32_e32 v70, v78
	v_mov_b32_e32 v71, v79
	s_waitcnt vmcnt(1)
	v_add_f32_e32 v6, v6, v7
	v_add_f32_e32 v7, v8, v9
	s_waitcnt vmcnt(0)
	v_add_f32_e32 v8, v10, v11
	v_add_f32_e32 v9, v12, v13
	v_add_f32_e32 v6, v6, v7
	v_add_f32_e32 v7, v8, v9
	v_add_f32_e32 v6, v6, v7
	v_fmamk_f32 v6, v6, 0x3b800000, v4
	s_cbranch_scc1 .LBB0_479
	v_mul_f32_e32 v7, 0x4f800000, v6
	v_cmp_gt_f32_e32 vcc, s24, v6
	s_nop 1
	v_cndmask_b32_e32 v7, v6, v7, vcc
	v_sqrt_f32_e32 v8, v7
	s_nop 0
	v_add_u32_e32 v9, -1, v8
	v_fma_f32 v11, -v9, v8, v7
	v_add_u32_e32 v10, 1, v8
	v_cmp_ge_f32_e64 s[0:1], 0, v11
	s_nop 1
	v_cndmask_b32_e64 v9, v8, v9, s[0:1]
	v_fma_f32 v8, -v10, v8, v7
	v_cmp_lt_f32_e64 s[0:1], 0, v8
	s_nop 1
	v_cndmask_b32_e64 v8, v9, v10, s[0:1]
	v_mul_f32_e32 v9, 0x37800000, v8
	v_cndmask_b32_e32 v8, v8, v9, vcc
	v_cmp_class_f32_e32 vcc, v7, v5
	s_nop 1
	v_cndmask_b32_e32 v7, v8, v7, vcc
	v_mul_f32_e32 v7, v145, v7
	ds_write_b32 v3, v7
	s_branch .LBB0_479
